# FFN-up conv3+SiLU epilogue loops rewritten by hand: wave-uniform row tests on SALU branches instead of per-lane compares and exec masks, scalar store base; next-tile L2 prefetch loads issued after the
# speedup vs baseline: 1.0446x; 1.0087x over previous
.LBB0_369:
	s_mov_b64 s[100:101], 0
	s_cmp_lg_u64 s[50:51], 0
	s_cbranch_scc0 .LBB0_375
	v_cmp_lt_i32_e64 s[20:21], s76, v193
	s_movk_i32 s4, 0x100
	v_cmp_gt_i32_e64 s[44:45], s4, v193
	s_mov_b64 s[46:47], s[20:21]
	s_and_saveexec_b64 s[22:23], s[44:45]
	v_cmp_ge_u32_sdwa s[40:41], v193, v194 src0_sel:BYTE_0 src1_sel:DWORD
	v_cmp_lt_i32_sdwa s[44:45], v193, s72 src0_sel:BYTE_0 src1_sel:DWORD
	s_and_b64 s[40:41], s[40:41], s[44:45]
	s_andn2_b64 s[44:45], s[20:21], exec
	s_and_b64 s[40:41], s[40:41], exec
	s_or_b64 s[46:47], s[44:45], s[40:41]
	s_or_b64 exec, exec, s[22:23]
	v_mov_b32_e32 v190, 0
	s_and_saveexec_b64 s[22:23], s[46:47]
	s_cbranch_execz .LBB0_374
	v_mov_b32_e32 v0, s51
	v_mov_b32_e32 v2, s31
	v_cndmask_b32_e64 v3, v0, v2, s[20:21]
	v_mov_b32_e32 v0, s50
	v_mov_b32_e32 v2, s30
	v_cndmask_b32_e64 v2, v0, v2, s[20:21]
	v_mov_b32_e32 v0, 11
	v_lshlrev_b32_sdwa v0, v0, v193 dst_sel:DWORD dst_unused:UNUSED_PAD src0_sel:DWORD src1_sel:BYTE_0
	v_lshl_add_u64 v[2:3], v[2:3], 0, v[0:1]
	v_mov_b32_e32 v212, v2
	v_mov_b32_e32 v213, v3
	s_mov_b64 s[100:101], exec

.LBB0_384:
	s_or_b64 exec, exec, s[22:23]
	v_mov_b32_e32 v0, v206
	v_mov_b32_e32 v2, v206
	s_waitcnt lgkmcnt(0)
	s_barrier
	s_load_dwordx4 s[48:51], s[0:1], 0xe8
	s_ashr_i32 s21, s20, 31
	v_lshlrev_b32_e32 v0, 1, v0
	s_lshl_b64 s[20:21], s[20:21], 1
	v_and_b32_e32 v193, 0x7e, v0
	s_waitcnt lgkmcnt(0)
	s_add_u32 s22, s50, s20
	v_ashrrev_i32_e32 v2, 2, v2
	s_movk_i32 s4, 0x7f
	s_addc_u32 s23, s51, s21
	v_lshlrev_b32_e32 v0, 1, v193
	v_and_b32_e32 v191, -16, v2
	s_mov_b32 s28, 0
	v_cmp_gt_i32_e64 s[44:45], 0, v2
	v_cmp_lt_u32_e64 s[46:47], s4, v2
	v_lshl_add_u64 v[188:189], s[22:23], 0, v[0:1]
	s_mov_b64 s[20:21], -1
	s_waitcnt vmcnt(0)
	s_mov_b64 exec, s[100:101]
	s_cbranch_execz .Lpfl_skip_up
	global_load_dword v190, v[212:213], off
	global_load_dword v190, v[212:213], off offset:128
.Lpfl_skip_up:
	s_mov_b64 exec, -1
	v_xor_b32_e32 v212, 32, v227
	v_xor_b32_e32 v213, 16, v227
	s_branch .LBB0_386
.LBB0_386:
	v_readfirstlane_b32 s21, v191
	s_mov_b32 s20, 0
.Lcva_hb:
	s_add_i32 s28, s21, s20
	v_lshlrev_b32_e32 v198, 2, v193
	s_add_i32 vcc_lo, s28, -1
	s_mulk_i32 vcc_lo, 0x410
	s_cmp_eq_u32 s28, 0
	s_cselect_b32 vcc_lo, 0x20400, vcc_lo
	v_add_u32_e32 v0, vcc_lo, v198
	ds_read2st64_b64 v[144:147], v0 offset1:1
	s_add_i32 vcc_lo, s28, 0
	s_mulk_i32 vcc_lo, 0x410
	v_add_u32_e32 v0, vcc_lo, v198
	ds_read2st64_b64 v[148:151], v0 offset1:1
	s_add_i32 vcc_lo, s28, 1
	s_mulk_i32 vcc_lo, 0x410
	v_add_u32_e32 v0, vcc_lo, v198
	ds_read2st64_b64 v[152:155], v0 offset1:1
	s_add_i32 vcc_lo, s28, 2
	s_mulk_i32 vcc_lo, 0x410
	v_add_u32_e32 v0, vcc_lo, v198
	ds_read2st64_b64 v[156:159], v0 offset1:1
	s_add_i32 vcc_lo, s28, 3
	s_mulk_i32 vcc_lo, 0x410
	v_add_u32_e32 v0, vcc_lo, v198
	ds_read2st64_b64 v[160:163], v0 offset1:1
	s_add_i32 vcc_lo, s28, 4
	s_mulk_i32 vcc_lo, 0x410
	v_add_u32_e32 v0, vcc_lo, v198
	ds_read2st64_b64 v[164:167], v0 offset1:1
	s_add_i32 vcc_lo, s28, 5
	s_mulk_i32 vcc_lo, 0x410
	v_add_u32_e32 v0, vcc_lo, v198
	ds_read2st64_b64 v[168:171], v0 offset1:1
	s_add_i32 vcc_lo, s28, 6
	s_mulk_i32 vcc_lo, 0x410
	v_add_u32_e32 v0, vcc_lo, v198
	ds_read2st64_b64 v[2:5], v0 offset1:1
	s_add_i32 vcc_lo, s28, 7
	s_mulk_i32 vcc_lo, 0x410
	v_add_u32_e32 v0, vcc_lo, v198
	ds_read2st64_b64 v[6:9], v0 offset1:1
	s_add_i32 vcc_lo, s28, 8
	s_mulk_i32 vcc_lo, 0x410
	s_cmpk_eq_u32 s28, 0x78
	s_cselect_b32 vcc_lo, 0x21000, vcc_lo
	v_add_u32_e32 v0, vcc_lo, v198
	ds_read2st64_b64 v[10:13], v0 offset1:1
	s_add_i32 s29, s81, s28
	s_cmp_ge_i32 s29, s74
	s_cbranch_scc1 .Lcvskipa_0
	s_cmp_eq_u32 s28, 0
	s_cbranch_scc1 .Lcvskipa_0
	s_waitcnt lgkmcnt(7)
	s_cmp_eq_u32 s29, s75
	s_cbranch_scc1 .Lcvspa_0
	v_pk_fma_f32 v[194:195], v[172:173], v[144:145], v[178:179]
	v_pk_fma_f32 v[196:197], v[180:181], v[146:147], v[186:187]
.Lcvsca_0:
	v_pk_fma_f32 v[194:195], v[174:175], v[148:149], v[194:195]
	v_pk_fma_f32 v[196:197], v[182:183], v[150:151], v[196:197]
	s_add_i32 vcc_lo, s29, 1
	s_cmp_eq_u32 vcc_lo, s75
	s_cbranch_scc1 .Lcvsna_0
	v_pk_fma_f32 v[194:195], v[176:177], v[152:153], v[194:195]
	v_pk_fma_f32 v[196:197], v[184:185], v[154:155], v[196:197]
.Lcvsna_0:
	v_mul_f32_e32 v198, 0xbfb8aa3b, v194
	v_mul_f32_e32 v199, 0xbfb8aa3b, v195
	v_exp_f32_e32 v198, v198
	v_exp_f32_e32 v199, v199
	s_add_i32 vcc_lo, s67, s29
	s_mul_i32 vcc_lo, vcc_lo, s93
	v_add_f32_e32 v198, 1.0, v198
	v_add_f32_e32 v199, 1.0, v199
	v_rcp_f32_e32 v198, v198
	v_rcp_f32_e32 v199, v199
	s_add_u32 s100, s22, vcc_lo
	s_addc_u32 s101, s23, 0
	v_mul_f32_e32 v194, v194, v198
	v_mul_f32_e32 v195, v195, v199
	v_mul_f32_e32 v194, v196, v194
	v_mul_f32_e32 v195, v197, v195
	v_lshlrev_b32_e32 v198, 1, v193
	v_cvt_pk_bf16_f32 v0, v194, v195
	global_store_dword v198, v0, s[100:101]
.Lcvskipa_0:
	s_add_i32 s29, s29, 1
	s_cmp_ge_i32 s29, s74
	s_cbranch_scc1 .Lcvskipa_1
	s_waitcnt lgkmcnt(6)
	s_cmp_eq_u32 s29, s75
	s_cbranch_scc1 .Lcvspa_1
	v_pk_fma_f32 v[194:195], v[172:173], v[148:149], v[178:179]
	v_pk_fma_f32 v[196:197], v[180:181], v[150:151], v[186:187]
.Lcvsca_1:
	v_pk_fma_f32 v[194:195], v[174:175], v[152:153], v[194:195]
	v_pk_fma_f32 v[196:197], v[182:183], v[154:155], v[196:197]
	s_add_i32 vcc_lo, s29, 1
	s_cmp_eq_u32 vcc_lo, s75
	s_cbranch_scc1 .Lcvsna_1
	v_pk_fma_f32 v[194:195], v[176:177], v[156:157], v[194:195]
	v_pk_fma_f32 v[196:197], v[184:185], v[158:159], v[196:197]

.Lcvskipa_1:
	s_add_i32 s29, s29, 1
	s_cmp_ge_i32 s29, s74
	s_cbranch_scc1 .Lcvskipa_2
	s_waitcnt lgkmcnt(5)
	s_cmp_eq_u32 s29, s75
	s_cbranch_scc1 .Lcvspa_2
	v_pk_fma_f32 v[194:195], v[172:173], v[152:153], v[178:179]
	v_pk_fma_f32 v[196:197], v[180:181], v[154:155], v[186:187]
.Lcvsca_2:
	v_pk_fma_f32 v[194:195], v[174:175], v[156:157], v[194:195]
	v_pk_fma_f32 v[196:197], v[182:183], v[158:159], v[196:197]
	s_add_i32 vcc_lo, s29, 1
	s_cmp_eq_u32 vcc_lo, s75
	s_cbranch_scc1 .Lcvsna_2
	v_pk_fma_f32 v[194:195], v[176:177], v[160:161], v[194:195]
	v_pk_fma_f32 v[196:197], v[184:185], v[162:163], v[196:197]

.Lcvskipa_2:
	s_add_i32 s29, s29, 1
	s_cmp_ge_i32 s29, s74
	s_cbranch_scc1 .Lcvskipa_3
	s_waitcnt lgkmcnt(4)
	s_cmp_eq_u32 s29, s75
	s_cbranch_scc1 .Lcvspa_3
	v_pk_fma_f32 v[194:195], v[172:173], v[156:157], v[178:179]
	v_pk_fma_f32 v[196:197], v[180:181], v[158:159], v[186:187]
.Lcvsca_3:
	v_pk_fma_f32 v[194:195], v[174:175], v[160:161], v[194:195]
	v_pk_fma_f32 v[196:197], v[182:183], v[162:163], v[196:197]
	s_add_i32 vcc_lo, s29, 1
	s_cmp_eq_u32 vcc_lo, s75
	s_cbranch_scc1 .Lcvsna_3
	v_pk_fma_f32 v[194:195], v[176:177], v[164:165], v[194:195]
	v_pk_fma_f32 v[196:197], v[184:185], v[166:167], v[196:197]

.Lcvskipa_3:
	s_add_i32 s29, s29, 1
	s_cmp_ge_i32 s29, s74
	s_cbranch_scc1 .Lcvskipa_4
	s_waitcnt lgkmcnt(3)
	s_cmp_eq_u32 s29, s75
	s_cbranch_scc1 .Lcvspa_4
	v_pk_fma_f32 v[194:195], v[172:173], v[160:161], v[178:179]
	v_pk_fma_f32 v[196:197], v[180:181], v[162:163], v[186:187]
.Lcvsca_4:
	v_pk_fma_f32 v[194:195], v[174:175], v[164:165], v[194:195]
	v_pk_fma_f32 v[196:197], v[182:183], v[166:167], v[196:197]
	s_add_i32 vcc_lo, s29, 1
	s_cmp_eq_u32 vcc_lo, s75
	s_cbranch_scc1 .Lcvsna_4
	v_pk_fma_f32 v[194:195], v[176:177], v[168:169], v[194:195]
	v_pk_fma_f32 v[196:197], v[184:185], v[170:171], v[196:197]

.Lcvskipa_4:
	s_add_i32 s29, s29, 1
	s_cmp_ge_i32 s29, s74
	s_cbranch_scc1 .Lcvskipa_5
	s_waitcnt lgkmcnt(2)
	s_cmp_eq_u32 s29, s75
	s_cbranch_scc1 .Lcvspa_5
	v_pk_fma_f32 v[194:195], v[172:173], v[164:165], v[178:179]
	v_pk_fma_f32 v[196:197], v[180:181], v[166:167], v[186:187]
.Lcvsca_5:
	v_pk_fma_f32 v[194:195], v[174:175], v[168:169], v[194:195]
	v_pk_fma_f32 v[196:197], v[182:183], v[170:171], v[196:197]
	s_add_i32 vcc_lo, s29, 1
	s_cmp_eq_u32 vcc_lo, s75
	s_cbranch_scc1 .Lcvsna_5
	v_pk_fma_f32 v[194:195], v[176:177], v[2:3], v[194:195]
	v_pk_fma_f32 v[196:197], v[184:185], v[4:5], v[196:197]

.Lcvskipa_5:
	s_add_i32 s29, s29, 1
	s_cmp_ge_i32 s29, s74
	s_cbranch_scc1 .Lcvskipa_6
	s_waitcnt lgkmcnt(1)
	s_cmp_eq_u32 s29, s75
	s_cbranch_scc1 .Lcvspa_6
	v_pk_fma_f32 v[194:195], v[172:173], v[168:169], v[178:179]
	v_pk_fma_f32 v[196:197], v[180:181], v[170:171], v[186:187]
.Lcvsca_6:
	v_pk_fma_f32 v[194:195], v[174:175], v[2:3], v[194:195]
	v_pk_fma_f32 v[196:197], v[182:183], v[4:5], v[196:197]
	s_add_i32 vcc_lo, s29, 1
	s_cmp_eq_u32 vcc_lo, s75
	s_cbranch_scc1 .Lcvsna_6
	v_pk_fma_f32 v[194:195], v[176:177], v[6:7], v[194:195]
	v_pk_fma_f32 v[196:197], v[184:185], v[8:9], v[196:197]

.Lcvskipa_6:
	s_add_i32 s29, s29, 1
	s_cmp_ge_i32 s29, s74
	s_cbranch_scc1 .Lcvskipa_7
	s_waitcnt lgkmcnt(0)
	s_cmp_eq_u32 s29, s75
	s_cbranch_scc1 .Lcvspa_7
	v_pk_fma_f32 v[194:195], v[172:173], v[2:3], v[178:179]
	v_pk_fma_f32 v[196:197], v[180:181], v[4:5], v[186:187]
.Lcvsca_7:
	v_pk_fma_f32 v[194:195], v[174:175], v[6:7], v[194:195]
	v_pk_fma_f32 v[196:197], v[182:183], v[8:9], v[196:197]
	s_add_i32 vcc_lo, s29, 1
	s_cmp_eq_u32 vcc_lo, s75
	s_cbranch_scc1 .Lcvsna_7
	v_pk_fma_f32 v[194:195], v[176:177], v[10:11], v[194:195]
	v_pk_fma_f32 v[196:197], v[184:185], v[12:13], v[196:197]

.Lcvskipa_7:
	s_waitcnt lgkmcnt(0)
	s_add_i32 s20, s20, 8
	s_cmp_lt_u32 s20, 16
	s_cbranch_scc1 .Lcva_hb
	s_branch .LBB0_406
.Lcvspa_0:
	v_mov_b32_e32 v194, v178
	v_mov_b32_e32 v195, v179
	v_mov_b32_e32 v196, v186
	v_mov_b32_e32 v197, v187
	s_branch .Lcvsca_0

.LBB0_410:
	v_readfirstlane_b32 s21, v44
	s_mov_b32 s20, 0
.Lcvb_hb:
	s_add_i32 s28, s21, s20
	v_lshlrev_b32_e32 v50, 2, v45
	s_add_i32 vcc_lo, s28, -1
	s_mulk_i32 vcc_lo, 0x410
	s_cmp_eq_u32 s28, 0
	s_cselect_b32 vcc_lo, 0x20c00, vcc_lo
	v_add_u32_e32 v0, vcc_lo, v50
	ds_read2st64_b64 v[2:5], v0 offset1:1
	s_add_i32 vcc_lo, s28, 0
	s_mulk_i32 vcc_lo, 0x410
	v_add_u32_e32 v0, vcc_lo, v50
	ds_read2st64_b64 v[6:9], v0 offset1:1
	s_add_i32 vcc_lo, s28, 1
	s_mulk_i32 vcc_lo, 0x410
	v_add_u32_e32 v0, vcc_lo, v50
	ds_read2st64_b64 v[10:13], v0 offset1:1
	s_add_i32 vcc_lo, s28, 2
	s_mulk_i32 vcc_lo, 0x410
	v_add_u32_e32 v0, vcc_lo, v50
	ds_read2st64_b64 v[14:17], v0 offset1:1
	s_add_i32 vcc_lo, s28, 3
	s_mulk_i32 vcc_lo, 0x410
	v_add_u32_e32 v0, vcc_lo, v50
	ds_read2st64_b64 v[18:21], v0 offset1:1
	s_add_i32 vcc_lo, s28, 4
	s_mulk_i32 vcc_lo, 0x410
	v_add_u32_e32 v0, vcc_lo, v50
	ds_read2st64_b64 v[22:25], v0 offset1:1
	s_add_i32 vcc_lo, s28, 5
	s_mulk_i32 vcc_lo, 0x410
	v_add_u32_e32 v0, vcc_lo, v50
	ds_read2st64_b64 v[26:29], v0 offset1:1
	s_add_i32 vcc_lo, s28, 6
	s_mulk_i32 vcc_lo, 0x410
	v_add_u32_e32 v0, vcc_lo, v50
	ds_read2st64_b64 v[30:33], v0 offset1:1
	s_add_i32 vcc_lo, s28, 7
	s_mulk_i32 vcc_lo, 0x410
	v_add_u32_e32 v0, vcc_lo, v50
	ds_read2st64_b64 v[34:37], v0 offset1:1
	s_add_i32 vcc_lo, s28, 8
	s_mulk_i32 vcc_lo, 0x410
	s_cmpk_eq_u32 s28, 0x78
	s_cselect_b32 vcc_lo, 0x21800, vcc_lo
	v_add_u32_e32 v0, vcc_lo, v50
	ds_read2st64_b64 v[38:41], v0 offset1:1
	s_add_i32 s29, s81, s28
	s_addk_i32 s29, 0x80
	s_cmp_ge_i32 s29, s74
	s_cbranch_scc1 .Lcvskipb_0
	s_waitcnt lgkmcnt(7)
	s_cmp_eq_u32 s29, s75
	s_cbranch_scc1 .Lcvspb_0
	v_pk_fma_f32 v[46:47], v[172:173], v[2:3], v[178:179]
	v_pk_fma_f32 v[48:49], v[180:181], v[4:5], v[186:187]
.Lcvscb_0:
	v_pk_fma_f32 v[46:47], v[174:175], v[6:7], v[46:47]
	v_pk_fma_f32 v[48:49], v[182:183], v[8:9], v[48:49]
	s_add_i32 vcc_lo, s29, 1
	s_cmp_eq_u32 vcc_lo, s75
	s_cbranch_scc1 .Lcvsnb_0
	v_pk_fma_f32 v[46:47], v[176:177], v[10:11], v[46:47]
	v_pk_fma_f32 v[48:49], v[184:185], v[12:13], v[48:49]
.Lcvsnb_0:
	v_mul_f32_e32 v50, 0xbfb8aa3b, v46
	v_mul_f32_e32 v51, 0xbfb8aa3b, v47
	v_exp_f32_e32 v50, v50
	v_exp_f32_e32 v51, v51
	s_add_i32 vcc_lo, s67, s29
	s_mul_i32 vcc_lo, vcc_lo, s93
	v_add_f32_e32 v50, 1.0, v50
	v_add_f32_e32 v51, 1.0, v51
	v_rcp_f32_e32 v50, v50
	v_rcp_f32_e32 v51, v51
	s_add_u32 s100, s22, vcc_lo
	s_addc_u32 s101, s23, 0
	v_mul_f32_e32 v46, v46, v50
	v_mul_f32_e32 v47, v47, v51
	v_mul_f32_e32 v46, v48, v46
	v_mul_f32_e32 v47, v49, v47
	v_lshlrev_b32_e32 v50, 1, v45
	v_cvt_pk_bf16_f32 v0, v46, v47
	global_store_dword v50, v0, s[100:101]
.Lcvskipb_0:
	s_add_i32 s29, s29, 1
	s_cmp_ge_i32 s29, s74
	s_cbranch_scc1 .Lcvskipb_1
	s_waitcnt lgkmcnt(6)
	s_cmp_eq_u32 s29, s75
	s_cbranch_scc1 .Lcvspb_1
	v_pk_fma_f32 v[46:47], v[172:173], v[6:7], v[178:179]
	v_pk_fma_f32 v[48:49], v[180:181], v[8:9], v[186:187]
.Lcvscb_1:
	v_pk_fma_f32 v[46:47], v[174:175], v[10:11], v[46:47]
	v_pk_fma_f32 v[48:49], v[182:183], v[12:13], v[48:49]
	s_add_i32 vcc_lo, s29, 1
	s_cmp_eq_u32 vcc_lo, s75
	s_cbranch_scc1 .Lcvsnb_1
	v_pk_fma_f32 v[46:47], v[176:177], v[14:15], v[46:47]
	v_pk_fma_f32 v[48:49], v[184:185], v[16:17], v[48:49]

.Lcvskipb_1:
	s_add_i32 s29, s29, 1
	s_cmp_ge_i32 s29, s74
	s_cbranch_scc1 .Lcvskipb_2
	s_waitcnt lgkmcnt(5)
	s_cmp_eq_u32 s29, s75
	s_cbranch_scc1 .Lcvspb_2
	v_pk_fma_f32 v[46:47], v[172:173], v[10:11], v[178:179]
	v_pk_fma_f32 v[48:49], v[180:181], v[12:13], v[186:187]
.Lcvscb_2:
	v_pk_fma_f32 v[46:47], v[174:175], v[14:15], v[46:47]
	v_pk_fma_f32 v[48:49], v[182:183], v[16:17], v[48:49]
	s_add_i32 vcc_lo, s29, 1
	s_cmp_eq_u32 vcc_lo, s75
	s_cbranch_scc1 .Lcvsnb_2
	v_pk_fma_f32 v[46:47], v[176:177], v[18:19], v[46:47]
	v_pk_fma_f32 v[48:49], v[184:185], v[20:21], v[48:49]

.Lcvskipb_2:
	s_add_i32 s29, s29, 1
	s_cmp_ge_i32 s29, s74
	s_cbranch_scc1 .Lcvskipb_3
	s_waitcnt lgkmcnt(4)
	s_cmp_eq_u32 s29, s75
	s_cbranch_scc1 .Lcvspb_3
	v_pk_fma_f32 v[46:47], v[172:173], v[14:15], v[178:179]
	v_pk_fma_f32 v[48:49], v[180:181], v[16:17], v[186:187]
.Lcvscb_3:
	v_pk_fma_f32 v[46:47], v[174:175], v[18:19], v[46:47]
	v_pk_fma_f32 v[48:49], v[182:183], v[20:21], v[48:49]
	s_add_i32 vcc_lo, s29, 1
	s_cmp_eq_u32 vcc_lo, s75
	s_cbranch_scc1 .Lcvsnb_3
	v_pk_fma_f32 v[46:47], v[176:177], v[22:23], v[46:47]
	v_pk_fma_f32 v[48:49], v[184:185], v[24:25], v[48:49]

.Lcvskipb_3:
	s_add_i32 s29, s29, 1
	s_cmp_ge_i32 s29, s74
	s_cbranch_scc1 .Lcvskipb_4
	s_waitcnt lgkmcnt(3)
	s_cmp_eq_u32 s29, s75
	s_cbranch_scc1 .Lcvspb_4
	v_pk_fma_f32 v[46:47], v[172:173], v[18:19], v[178:179]
	v_pk_fma_f32 v[48:49], v[180:181], v[20:21], v[186:187]
.Lcvscb_4:
	v_pk_fma_f32 v[46:47], v[174:175], v[22:23], v[46:47]
	v_pk_fma_f32 v[48:49], v[182:183], v[24:25], v[48:49]
	s_add_i32 vcc_lo, s29, 1
	s_cmp_eq_u32 vcc_lo, s75
	s_cbranch_scc1 .Lcvsnb_4
	v_pk_fma_f32 v[46:47], v[176:177], v[26:27], v[46:47]
	v_pk_fma_f32 v[48:49], v[184:185], v[28:29], v[48:49]

.Lcvskipb_4:
	s_add_i32 s29, s29, 1
	s_cmp_ge_i32 s29, s74
	s_cbranch_scc1 .Lcvskipb_5
	s_waitcnt lgkmcnt(2)
	s_cmp_eq_u32 s29, s75
	s_cbranch_scc1 .Lcvspb_5
	v_pk_fma_f32 v[46:47], v[172:173], v[22:23], v[178:179]
	v_pk_fma_f32 v[48:49], v[180:181], v[24:25], v[186:187]
.Lcvscb_5:
	v_pk_fma_f32 v[46:47], v[174:175], v[26:27], v[46:47]
	v_pk_fma_f32 v[48:49], v[182:183], v[28:29], v[48:49]
	s_add_i32 vcc_lo, s29, 1
	s_cmp_eq_u32 vcc_lo, s75
	s_cbranch_scc1 .Lcvsnb_5
	v_pk_fma_f32 v[46:47], v[176:177], v[30:31], v[46:47]
	v_pk_fma_f32 v[48:49], v[184:185], v[32:33], v[48:49]

.Lcvskipb_5:
	s_add_i32 s29, s29, 1
	s_cmp_ge_i32 s29, s74
	s_cbranch_scc1 .Lcvskipb_6
	s_waitcnt lgkmcnt(1)
	s_cmp_eq_u32 s29, s75
	s_cbranch_scc1 .Lcvspb_6
	v_pk_fma_f32 v[46:47], v[172:173], v[26:27], v[178:179]
	v_pk_fma_f32 v[48:49], v[180:181], v[28:29], v[186:187]
.Lcvscb_6:
	v_pk_fma_f32 v[46:47], v[174:175], v[30:31], v[46:47]
	v_pk_fma_f32 v[48:49], v[182:183], v[32:33], v[48:49]
	s_add_i32 vcc_lo, s29, 1
	s_cmp_eq_u32 vcc_lo, s75
	s_cbranch_scc1 .Lcvsnb_6
	v_pk_fma_f32 v[46:47], v[176:177], v[34:35], v[46:47]
	v_pk_fma_f32 v[48:49], v[184:185], v[36:37], v[48:49]

.Lcvskipb_6:
	s_add_i32 s29, s29, 1
	s_cmp_ge_i32 s29, s74
	s_cbranch_scc1 .Lcvskipb_7
	s_cmpk_eq_u32 s28, 0x78
	s_cbranch_scc1 .Lcvskipb_7
	s_waitcnt lgkmcnt(0)
	s_cmp_eq_u32 s29, s75
	s_cbranch_scc1 .Lcvspb_7
	v_pk_fma_f32 v[46:47], v[172:173], v[30:31], v[178:179]
	v_pk_fma_f32 v[48:49], v[180:181], v[32:33], v[186:187]
.Lcvscb_7:
	v_pk_fma_f32 v[46:47], v[174:175], v[34:35], v[46:47]
	v_pk_fma_f32 v[48:49], v[182:183], v[36:37], v[48:49]
	s_add_i32 vcc_lo, s29, 1
	s_cmp_eq_u32 vcc_lo, s75
	s_cbranch_scc1 .Lcvsnb_7
	v_pk_fma_f32 v[46:47], v[176:177], v[38:39], v[46:47]
	v_pk_fma_f32 v[48:49], v[184:185], v[40:41], v[48:49]

.Lcvspb_0:
	v_mov_b32_e32 v46, v178
	v_mov_b32_e32 v47, v179
	v_mov_b32_e32 v48, v186
	v_mov_b32_e32 v49, v187
	s_branch .Lcvscb_0
